# prep phase: q and kv latent loads issued with the first window batch (one round trip fewer per row); merge hook trailing gate loads before the wait
# baseline (speedup 1.0000x reference)
; __device__ __forceinline__ unsigned cvt_pk_bf16(float lo, float hi) { const f32x2_ v = {lo, hi}; return __builtin_bit_cast(unsigned, __builtin_convertvector(v, bf16x2_)); }
; __device__ __forceinline__ float bf_lo(unsigned u) { return __uint_as_float(u << 16); }
; __device__ __forceinline__ float bf_hi(unsigned u) { return __uint_as_float(u & 0xffff0000u); }
; __device__ void prep_phase(PK p) {
;     ...
;             const int wdw = 2 << (lane >> 4), hw = wdw >> 1; const int lo = max(t - hw, 0), hi = min(t + hw, n);
;             float s0 = 0.f, s1 = 0.f, s2 = 0.f, s3 = 0.f;
; #pragma unroll
;             for (int i = 0; i < 16; ++i) {
;                 const int off = i - 8, tt = t + off; const bool ok = (off >= -hw) && (off < hw) && (tt >= 0) && (tt < n);
;                 const u32x2 v = *(const u32x2*)(PJ + (size_t)(sbase + (ok ? tt : t)) * PJW + 4 * lane); const float wg = ok ? 1.0f : 0.0f;
;                 s0 += wg * bf_lo(v.x); s1 += wg * bf_hi(v.x); s2 += wg * bf_lo(v.y); s3 += wg * bf_hi(v.y); }
;             const float ic = 1.0f / (float)(hi - lo); const u32x2 sv = *(const u32x2*)(prow + 4 * lane);
;             u32x2 w; w.x = cvt_pk_bf16(s0 * ic - bf_lo(sv.x), s1 * ic - bf_hi(sv.x)); w.y = cvt_pk_bf16(s2 * ic - bf_lo(sv.y), s3 * ic - bf_hi(sv.y));
;             *(u32x2*)(YB + (size_t)row * 1024 + 4 * lane) = w;
;         }
;         {
;             const u32x2 q = *(const u32x2*)(prow + C_MQ + 4 * lane); const unsigned kv = *(const unsigned*)(prow + C_MKV + 2 * lane);
.LBB0_489:
	v_cmp_gt_i32_e64 s[18:19], s95, v14
	v_and_b32_e32 v7, 0x1fff, v14
	v_and_b32_e32 v2, 0xff, v14
	v_mov_b32_e32 v3, 0x2000
	s_waitcnt lgkmcnt(0)
	v_mov_b32_e32 v4, 0x100
	v_cndmask_b32_e64 v37, v2, v7, s[18:19]
	v_cndmask_b32_e64 v15, v4, v3, s[18:19]
	v_add_u32_e32 v2, -8, v37
	v_cmp_lt_u32_e32 vcc, v2, v15
	s_and_b64 vcc, s[14:15], vcc
	v_add_u32_e32 v4, -7, v37
	v_cndmask_b32_e32 v2, v37, v2, vcc
	v_cndmask_b32_e64 v6, 0, 1.0, vcc
	v_cmp_lt_u32_e32 vcc, v4, v15
	s_and_b64 vcc, s[14:15], vcc
	v_sub_u32_e32 v2, v2, v37
	v_cndmask_b32_e32 v4, v37, v4, vcc
	v_sub_u32_e32 v4, v4, v37
	v_add_u32_e32 v2, v14, v2
	v_add_u32_e32 v4, v14, v4
	v_mad_i64_i32 v[2:3], s[0:1], v2, s56, v[16:17]
	v_mad_i64_i32 v[4:5], s[0:1], v4, s56, v[16:17]
	global_load_dwordx2 v[2:3], v[2:3], off
	v_cndmask_b32_e64 v10, 0, 1.0, vcc
	global_load_dwordx2 v[8:9], v[4:5], off
	v_add_u32_e32 v4, -6, v37
	v_cmp_lt_u32_e32 vcc, v4, v15
	s_and_b64 vcc, s[14:15], vcc
	v_readlane_b32 s2, v254, 56
	v_cndmask_b32_e32 v4, v37, v4, vcc
	v_sub_u32_e32 v4, v4, v37
	v_add_u32_e32 v4, v14, v4
	v_mad_i64_i32 v[4:5], s[0:1], v4, s56, v[16:17]
	global_load_dwordx2 v[12:13], v[4:5], off
	v_add_u32_e32 v4, -5, v37
	v_cndmask_b32_e64 v34, 0, 1.0, vcc
	v_cmp_lt_u32_e32 vcc, v4, v15
	s_and_b64 vcc, s[14:15], vcc
	v_readlane_b32 s3, v254, 57
	v_cndmask_b32_e32 v4, v37, v4, vcc
	v_sub_u32_e32 v4, v4, v37
	v_add_u32_e32 v4, v14, v4
	v_mad_i64_i32 v[4:5], s[0:1], v4, s56, v[16:17]
	global_load_dwordx2 v[38:39], v[4:5], off
	v_add_u32_e32 v4, -4, v37
	v_cndmask_b32_e64 v36, 0, 1.0, vcc
	v_cmp_lt_u32_e32 vcc, v4, v15
	s_and_b64 vcc, s[8:9], vcc
	v_sub_u32_e32 v19, v37, v1
	v_cndmask_b32_e32 v4, v37, v4, vcc
	v_sub_u32_e32 v4, v4, v37
	v_add_u32_e32 v4, v14, v4
	v_mad_i64_i32 v[4:5], s[0:1], v4, s56, v[16:17]
	global_load_dwordx2 v[40:41], v[4:5], off
	v_add_u32_e32 v4, -3, v37
	v_cndmask_b32_e64 v42, 0, 1.0, vcc
	v_cmp_lt_u32_e32 vcc, v4, v15
	s_and_b64 vcc, s[8:9], vcc
	v_add_u32_e32 v33, v37, v1
	v_cndmask_b32_e32 v4, v37, v4, vcc
	v_sub_u32_e32 v4, v4, v37
	v_add_u32_e32 v4, v14, v4
	v_mad_i64_i32 v[4:5], s[0:1], v4, s56, v[16:17]
	global_load_dwordx2 v[44:45], v[4:5], off
	v_add_u32_e32 v4, -2, v37
	v_cndmask_b32_e64 v46, 0, 1.0, vcc
	v_cmp_lt_u32_e32 vcc, v4, v15
	s_and_b64 vcc, s[16:17], vcc
	v_max_i32_e32 v19, 0, v19
	v_cndmask_b32_e32 v4, v37, v4, vcc
	v_sub_u32_e32 v4, v4, v37
	v_add_u32_e32 v4, v14, v4
	v_mad_i64_i32 v[4:5], s[0:1], v4, s56, v[16:17]
	global_load_dwordx2 v[48:49], v[4:5], off
	v_cndmask_b32_e64 v50, 0, 1.0, vcc
	s_mov_b32 s98, 0x78de000
	s_mov_b32 s99, 0
	v_lshl_add_u64 v[80:81], s[2:3], 0, v[24:25]
	v_lshl_add_u64 v[84:85], s[2:3], 0, v[30:31]
	v_lshl_add_u64 v[80:81], v[80:81], 0, s[98:99]
	global_load_dword v86, v[84:85], off
	global_load_dwordx2 v[82:83], v[80:81], off offset:3584
	s_waitcnt vmcnt(2)
	v_lshlrev_b32_e32 v4, 16, v2
	v_and_b32_e32 v5, 0xffff0000, v2
	v_lshlrev_b32_e32 v2, 16, v3
	v_and_b32_e32 v3, 0xffff0000, v3
	v_lshlrev_b32_e32 v52, 16, v8
	v_and_b32_e32 v53, 0xffff0000, v8
	v_pk_fma_f32 v[2:3], v[6:7], v[2:3], 0 op_sel_hi:[0,1,0]
	v_lshlrev_b32_e32 v8, 16, v9
	v_and_b32_e32 v9, 0xffff0000, v9
	v_pk_fma_f32 v[4:5], v[6:7], v[4:5], 0 op_sel_hi:[0,1,0]
	v_pk_fma_f32 v[2:3], v[10:11], v[8:9], v[2:3] op_sel_hi:[0,1,1]
	v_add_u32_e32 v6, -1, v37
	v_lshlrev_b32_e32 v8, 16, v13
	v_and_b32_e32 v9, 0xffff0000, v13
	v_pk_fma_f32 v[2:3], v[34:35], v[8:9], v[2:3] op_sel_hi:[0,1,1]
	v_cmp_lt_u32_e32 vcc, v6, v15
	v_pk_fma_f32 v[4:5], v[10:11], v[52:53], v[4:5] op_sel_hi:[0,1,1]
	v_lshlrev_b32_e32 v52, 16, v12
	v_cndmask_b32_e32 v6, v37, v6, vcc
	v_and_b32_e32 v53, 0xffff0000, v12
	v_sub_u32_e32 v6, v6, v37
	v_pk_fma_f32 v[4:5], v[34:35], v[52:53], v[4:5] op_sel_hi:[0,1,1]
	v_add_u32_e32 v6, v14, v6
	v_lshlrev_b32_e32 v8, 16, v39
	v_and_b32_e32 v9, 0xffff0000, v39
	v_pk_fma_f32 v[2:3], v[36:37], v[8:9], v[2:3] op_sel_hi:[0,1,1]
	v_lshlrev_b32_e32 v52, 16, v38
	v_and_b32_e32 v53, 0xffff0000, v38
	v_pk_fma_f32 v[4:5], v[36:37], v[52:53], v[4:5] op_sel_hi:[0,1,1]
	v_lshl_add_u64 v[10:11], s[2:3], 0, v[24:25]
	v_lshlrev_b32_e32 v8, 16, v41
	v_and_b32_e32 v9, 0xffff0000, v41
	v_pk_fma_f32 v[2:3], v[42:43], v[8:9], v[2:3] op_sel_hi:[0,1,1]
	v_lshlrev_b32_e32 v52, 16, v40
	v_and_b32_e32 v53, 0xffff0000, v40
	v_add_u32_e32 v40, 1, v37
	v_pk_fma_f32 v[4:5], v[42:43], v[52:53], v[4:5] op_sel_hi:[0,1,1]
	v_lshlrev_b32_e32 v8, 16, v45
	v_and_b32_e32 v9, 0xffff0000, v45
	v_pk_fma_f32 v[2:3], v[46:47], v[8:9], v[2:3] op_sel_hi:[0,1,1]
	v_lshlrev_b32_e32 v52, 16, v44
	v_and_b32_e32 v53, 0xffff0000, v44
	v_pk_fma_f32 v[4:5], v[46:47], v[52:53], v[4:5] op_sel_hi:[0,1,1]
	v_lshlrev_b32_e32 v8, 16, v49
	v_and_b32_e32 v9, 0xffff0000, v49
	v_pk_fma_f32 v[2:3], v[50:51], v[8:9], v[2:3] op_sel_hi:[0,1,1]
	v_mad_i64_i32 v[8:9], s[0:1], v6, s56, v[16:17]
	v_cndmask_b32_e64 v6, 0, 1.0, vcc
	v_cmp_lt_u32_e32 vcc, v37, v15
	s_mov_b32 s0, 0x78de000
	v_add_co_u32_e64 v10, s[20:21], s0, v10
	v_cndmask_b32_e64 v36, 0, 1.0, vcc
	v_cmp_lt_u32_e32 vcc, v40, v15
	s_and_b64 vcc, s[16:17], vcc
	v_addc_co_u32_e64 v11, s[20:21], 0, v11, s[20:21]
	v_cndmask_b32_e32 v40, v37, v40, vcc
	v_sub_u32_e32 v40, v40, v37
	v_add_u32_e32 v40, v14, v40
	v_mad_i64_i32 v[40:41], s[0:1], v40, s56, v[16:17]
	global_load_dwordx2 v[8:9], v[8:9], off
	v_lshlrev_b32_e32 v52, 16, v48
	global_load_dwordx2 v[12:13], v[10:11], off
	global_load_dwordx2 v[42:43], v[40:41], off
	v_add_u32_e32 v41, 2, v37
	v_cndmask_b32_e64 v40, 0, 1.0, vcc
	v_cmp_lt_u32_e32 vcc, v41, v15
	s_and_b64 vcc, s[8:9], vcc
	v_and_b32_e32 v53, 0xffff0000, v48
	v_cndmask_b32_e32 v41, v37, v41, vcc
	v_sub_u32_e32 v41, v41, v37
	v_add_u32_e32 v41, v14, v41
	v_mad_i64_i32 v[44:45], s[0:1], v41, s56, v[16:17]
	v_add_u32_e32 v41, 3, v37
	global_load_dwordx2 v[46:47], v[44:45], off
	v_cndmask_b32_e64 v44, 0, 1.0, vcc
	v_cmp_lt_u32_e32 vcc, v41, v15
	s_and_b64 vcc, s[8:9], vcc
	v_pk_fma_f32 v[4:5], v[50:51], v[52:53], v[4:5] op_sel_hi:[0,1,1]
	v_cndmask_b32_e32 v41, v37, v41, vcc
	v_sub_u32_e32 v41, v41, v37
	v_add_u32_e32 v41, v14, v41
	v_mad_i64_i32 v[50:51], s[0:1], v41, s56, v[16:17]
	v_add_u32_e32 v41, 4, v37
	global_load_dwordx2 v[52:53], v[50:51], off
	v_cndmask_b32_e64 v50, 0, 1.0, vcc
	v_cmp_lt_u32_e32 vcc, v41, v15
	s_and_b64 vcc, s[14:15], vcc
	s_waitcnt vmcnt(0)
; __device__ __forceinline__ unsigned cvt_pk_bf16(float lo, float hi) { const f32x2_ v = {lo, hi}; return __builtin_bit_cast(unsigned, __builtin_convertvector(v, bf16x2_)); }
; __device__ __forceinline__ float bf_lo(unsigned u) { return __uint_as_float(u << 16); }
; __device__ __forceinline__ float bf_hi(unsigned u) { return __uint_as_float(u & 0xffff0000u); }
; __device__ void prep_phase(PK p) {
;     ...
;             for (int i = 0; i < 16; ++i) {
;                 const int off = i - 8, tt = t + off; const bool ok = (off >= -hw) && (off < hw) && (tt >= 0) && (tt < n);
;                 const u32x2 v = *(const u32x2*)(PJ + (size_t)(sbase + (ok ? tt : t)) * PJW + 4 * lane); const float wg = ok ? 1.0f : 0.0f;
;                 s0 += wg * bf_lo(v.x); s1 += wg * bf_hi(v.x); s2 += wg * bf_lo(v.y); s3 += wg * bf_hi(v.y); }
;             const float ic = 1.0f / (float)(hi - lo); const u32x2 sv = *(const u32x2*)(prow + 4 * lane);
;             u32x2 w; w.x = cvt_pk_bf16(s0 * ic - bf_lo(sv.x), s1 * ic - bf_hi(sv.x)); w.y = cvt_pk_bf16(s2 * ic - bf_lo(sv.y), s3 * ic - bf_hi(sv.y));
;             *(u32x2*)(YB + (size_t)row * 1024 + 4 * lane) = w;
;         }
;         {
;             const u32x2 q = *(const u32x2*)(prow + C_MQ + 4 * lane); const unsigned kv = *(const unsigned*)(prow + C_MKV + 2 * lane);
;             float sq = bf_lo(q.x) * bf_lo(q.x) + bf_hi(q.x) * bf_hi(q.x) + bf_lo(q.y) * bf_lo(q.y) + bf_hi(q.y) * bf_hi(q.y);
;             float sk = bf_lo(kv) * bf_lo(kv) + bf_hi(kv) * bf_hi(kv);
;             sq = wave_sum(sq); sk = wave_sum(sk);
	v_lshlrev_b32_e32 v34, 16, v8
	v_cndmask_b32_e32 v41, v37, v41, vcc
	v_sub_u32_e32 v41, v41, v37
	v_add_u32_e32 v41, v14, v41
	v_mad_i64_i32 v[54:55], s[0:1], v41, s56, v[16:17]
	v_add_u32_e32 v41, 5, v37
	global_load_dwordx2 v[56:57], v[54:55], off
	v_cndmask_b32_e64 v54, 0, 1.0, vcc
	v_cmp_lt_u32_e32 vcc, v41, v15
	s_and_b64 vcc, s[14:15], vcc
	v_and_b32_e32 v35, 0xffff0000, v8
	v_cndmask_b32_e32 v41, v37, v41, vcc
	v_sub_u32_e32 v41, v41, v37
	v_add_u32_e32 v41, v14, v41
	v_mad_i64_i32 v[60:61], s[0:1], v41, s56, v[16:17]
	v_add_u32_e32 v41, 6, v37
	global_load_dwordx2 v[62:63], v[60:61], off
	v_cndmask_b32_e64 v60, 0, 1.0, vcc
	v_cmp_lt_u32_e32 vcc, v41, v15
	s_and_b64 vcc, s[14:15], vcc
	v_lshlrev_b32_e32 v8, 16, v9
	v_cndmask_b32_e32 v41, v37, v41, vcc
	v_sub_u32_e32 v41, v41, v37
	v_add_u32_e32 v41, v14, v41
	v_mad_i64_i32 v[64:65], s[0:1], v41, s56, v[16:17]
	v_add_u32_e32 v41, 7, v37
	global_load_dwordx2 v[66:67], v[64:65], off
	v_cndmask_b32_e64 v64, 0, 1.0, vcc
	v_cmp_lt_u32_e32 vcc, v41, v15
	s_and_b64 vcc, s[14:15], vcc
	v_min_u32_e32 v15, v33, v15
	v_cndmask_b32_e32 v41, v37, v41, vcc
	v_sub_u32_e32 v37, v41, v37
	v_add_u32_e32 v37, v14, v37
	v_mad_i64_i32 v[68:69], s[0:1], v37, s56, v[16:17]
	global_load_dwordx2 v[70:71], v[68:69], off
	v_sub_u32_e32 v15, v15, v19
	v_cvt_f32_i32_e32 v15, v15
	v_cndmask_b32_e64 v68, 0, 1.0, vcc
	v_and_b32_e32 v9, 0xffff0000, v9
	v_lshlrev_b32_e32 v38, 16, v12
	v_div_scale_f32 v19, s[0:1], v15, v15, 1.0
	v_rcp_f32_e32 v33, v19
	v_and_b32_e32 v39, 0xffff0000, v12
	v_lshlrev_b32_e32 v12, 16, v13
	v_and_b32_e32 v13, 0xffff0000, v13
	v_fma_f32 v37, -v19, v33, 1.0
	v_fmac_f32_e32 v33, v37, v33
	v_div_scale_f32 v37, vcc, 1.0, v15, 1.0
	v_mul_f32_e32 v41, v37, v33
	v_fma_f32 v45, -v19, v41, v37
	v_pk_fma_f32 v[4:5], v[6:7], v[34:35], v[4:5] op_sel_hi:[0,1,1]
	v_pk_fma_f32 v[2:3], v[6:7], v[8:9], v[2:3] op_sel_hi:[0,1,1]
	v_lshlrev_b32_e32 v48, 16, v42
	v_and_b32_e32 v49, 0xffff0000, v42
	v_lshlrev_b32_e32 v42, 16, v43
	v_and_b32_e32 v43, 0xffff0000, v43
	v_fmac_f32_e32 v41, v45, v33
	v_pk_fma_f32 v[4:5], v[36:37], v[38:39], v[4:5] op_sel_hi:[0,1,1]
	v_pk_fma_f32 v[2:3], v[36:37], v[12:13], v[2:3] op_sel_hi:[0,1,1]
	v_lshlrev_b32_e32 v58, 16, v46
	v_and_b32_e32 v59, 0xffff0000, v46
	v_lshlrev_b32_e32 v46, 16, v47
	v_and_b32_e32 v47, 0xffff0000, v47
	v_pk_fma_f32 v[4:5], v[40:41], v[48:49], v[4:5] op_sel_hi:[0,1,1]
	v_pk_fma_f32 v[2:3], v[40:41], v[42:43], v[2:3] op_sel_hi:[0,1,1]
	v_pk_fma_f32 v[4:5], v[44:45], v[58:59], v[4:5] op_sel_hi:[0,1,1]
	v_lshlrev_b32_e32 v34, 16, v52
	v_and_b32_e32 v35, 0xffff0000, v52
	v_pk_fma_f32 v[2:3], v[44:45], v[46:47], v[2:3] op_sel_hi:[0,1,1]
	v_lshlrev_b32_e32 v8, 16, v53
	v_and_b32_e32 v9, 0xffff0000, v53
	v_pk_fma_f32 v[4:5], v[50:51], v[34:35], v[4:5] op_sel_hi:[0,1,1]
	v_pk_fma_f32 v[2:3], v[50:51], v[8:9], v[2:3] op_sel_hi:[0,1,1]
	v_fma_f32 v19, -v19, v41, v37
	v_div_fmas_f32 v19, v19, v33, v41
	v_div_fixup_f32 v72, v19, v15, 1.0
	v_mov_b32_e32 v15, v220
	v_mov_b32_e32 v19, v220
	v_mov_b32_e32 v33, v220
	s_waitcnt vmcnt(0)
	v_lshlrev_b32_e32 v34, 16, v56
	v_and_b32_e32 v35, 0xffff0000, v56
	v_lshlrev_b32_e32 v8, 16, v57
	v_and_b32_e32 v9, 0xffff0000, v57
	v_pk_fma_f32 v[4:5], v[54:55], v[34:35], v[4:5] op_sel_hi:[0,1,1]
	v_pk_fma_f32 v[2:3], v[54:55], v[8:9], v[2:3] op_sel_hi:[0,1,1]
	v_lshlrev_b32_e32 v34, 16, v62
	v_and_b32_e32 v35, 0xffff0000, v62
	v_lshlrev_b32_e32 v8, 16, v63
	v_and_b32_e32 v9, 0xffff0000, v63
	v_pk_fma_f32 v[4:5], v[60:61], v[34:35], v[4:5] op_sel_hi:[0,1,1]
	v_pk_fma_f32 v[2:3], v[60:61], v[8:9], v[2:3] op_sel_hi:[0,1,1]
	v_lshlrev_b32_e32 v34, 16, v66
	v_and_b32_e32 v35, 0xffff0000, v66
	v_lshlrev_b32_e32 v8, 16, v67
	v_and_b32_e32 v9, 0xffff0000, v67
	v_pk_fma_f32 v[4:5], v[64:65], v[34:35], v[4:5] op_sel_hi:[0,1,1]
	v_pk_fma_f32 v[2:3], v[64:65], v[8:9], v[2:3] op_sel_hi:[0,1,1]
	v_lshlrev_b32_e32 v34, 16, v70
	v_and_b32_e32 v35, 0xffff0000, v70
	v_lshlrev_b32_e32 v8, 16, v71
	v_and_b32_e32 v9, 0xffff0000, v71
	v_pk_fma_f32 v[4:5], v[68:69], v[34:35], v[4:5] op_sel_hi:[0,1,1]
	v_pk_fma_f32 v[2:3], v[68:69], v[8:9], v[2:3] op_sel_hi:[0,1,1]
	v_pk_fma_f32 v[4:5], v[72:73], v[4:5], v[38:39] op_sel_hi:[0,1,1] neg_lo:[0,0,1] neg_hi:[0,0,1]
	v_pk_fma_f32 v[2:3], v[72:73], v[2:3], v[12:13] op_sel_hi:[0,1,1] neg_lo:[0,0,1] neg_hi:[0,0,1]
	v_cvt_pk_bf16_f32 v4, v4, v5
	v_cvt_pk_bf16_f32 v5, v2, v3
	v_lshl_add_u64 v[2:3], s[2:3], 0, v[22:23]
	global_store_dwordx2 v[2:3], v[4:5], off
	v_mov_b32_e32 v2, v82
	v_mov_b32_e32 v3, v83
	v_mov_b32_e32 v6, v86
	v_mov_b32_e32 v9, v220
	v_mov_b32_e32 v10, v220
	v_mov_b32_e32 v11, v220
	v_mov_b32_e32 v12, v220
	v_mov_b32_e32 v13, v220
	v_mov_b32_e32 v34, v220
	v_lshlrev_b32_e32 v5, 16, v3
	v_lshlrev_b32_e32 v4, 16, v2
	v_and_b32_e32 v8, 0xffff0000, v2
	v_pk_mul_f32 v[4:5], v[4:5], v[4:5]
	s_nop 0
	v_fma_f32 v2, v8, v8, v4
	v_add_f32_e32 v2, v5, v2
	v_and_b32_e32 v4, 0xffff0000, v3
	v_lshlrev_b32_e32 v5, 16, v6
	v_and_b32_e32 v3, 0xffff0000, v6
	v_mov_b32_e32 v6, v220
	v_mov_b32_e32 v8, v220
	v_mul_f32_e32 v3, v3, v3
	v_lshlrev_b32_e32 v6, 2, v6
	v_lshlrev_b32_e32 v13, 2, v13
	v_xor_b32_e32 v6, 0x80, v6
	v_xor_b32_e32 v13, 0x80, v13
	v_pk_fma_f32 v[2:3], v[4:5], v[4:5], v[2:3]
	ds_bpermute_b32 v4, v6, v2
	ds_bpermute_b32 v5, v13, v3
	v_lshlrev_b32_e32 v8, 2, v8
	v_lshlrev_b32_e32 v15, 2, v15
	v_xor_b32_e32 v8, 64, v8
	v_xor_b32_e32 v15, 64, v15
	s_waitcnt lgkmcnt(0)
	v_pk_add_f32 v[2:3], v[2:3], v[4:5]
	ds_bpermute_b32 v4, v8, v2
	ds_bpermute_b32 v5, v15, v3
	v_lshlrev_b32_e32 v9, 2, v9
	v_lshlrev_b32_e32 v19, 2, v19
	v_xor_b32_e32 v9, 32, v9
	v_xor_b32_e32 v19, 32, v19
	s_waitcnt lgkmcnt(0)
	v_pk_add_f32 v[2:3], v[2:3], v[4:5]
	ds_bpermute_b32 v4, v9, v2
	ds_bpermute_b32 v5, v19, v3
	v_lshlrev_b32_e32 v10, 2, v10
	v_lshlrev_b32_e32 v33, 2, v33
	v_xor_b32_e32 v10, 16, v10
	v_xor_b32_e32 v33, 16, v33
	s_waitcnt lgkmcnt(0)
	v_pk_add_f32 v[2:3], v[2:3], v[4:5]
	ds_bpermute_b32 v4, v10, v2
	ds_bpermute_b32 v5, v33, v3
	v_lshlrev_b32_e32 v11, 2, v11
	v_lshlrev_b32_e32 v34, 2, v34
	v_xor_b32_e32 v11, 8, v11
	v_xor_b32_e32 v34, 8, v34
	s_waitcnt lgkmcnt(0)
	v_pk_add_f32 v[2:3], v[2:3], v[4:5]
	ds_bpermute_b32 v4, v11, v2
	ds_bpermute_b32 v5, v34, v3
	v_lshlrev_b32_e32 v12, 2, v12
	v_xor_b32_e32 v12, 4, v12
	s_waitcnt lgkmcnt(0)
	v_pk_add_f32 v[2:3], v[2:3], v[4:5]
	v_mov_b32_e32 v5, v220
	ds_bpermute_b32 v4, v12, v2
	v_lshlrev_b32_e32 v5, 2, v5
	v_xor_b32_e32 v5, 4, v5
	ds_bpermute_b32 v5, v5, v3
	s_and_saveexec_b64 s[0:1], s[4:5]
	s_cbranch_execz .LBB0_491
; __device__ void prep_phase(PK p) {
;     ...
;             if (lane == 0) { RSTD[row * 2] = rsqrtf(sq * (1.0f / 256.0f) + NEPS); RSTD[row * 2 + 1] = rsqrtf(sk * (1.0f / 128.0f) + NEPS); }
	s_waitcnt lgkmcnt(0)
	v_pk_add_f32 v[2:3], v[2:3], v[4:5]
	s_mov_b32 s2, 0x45800000
	v_pk_fma_f32 v[2:3], v[2:3], s[86:87], v[188:189] op_sel_hi:[1,1,0]
	v_ashrrev_i32_e32 v19, 31, v18
	v_mul_f32_e32 v4, 0x4b800000, v2
	v_cmp_gt_f32_e64 s[20:21], s44, v2
	v_cmp_gt_f32_e32 vcc, s44, v3
	v_lshl_add_u64 v[8:9], v[18:19], 2, s[24:25]
	v_cndmask_b32_e64 v2, v2, v4, s[20:21]
	v_mul_f32_e32 v4, 0x4b800000, v3
	v_cndmask_b32_e32 v3, v3, v4, vcc
	v_rsq_f32_e32 v2, v2
	v_rsq_f32_e32 v3, v3
	s_nop 0
	v_pk_mul_f32 v[4:5], v[2:3], s[2:3] op_sel_hi:[1,0]
	s_nop 0
	v_cndmask_b32_e32 v3, v3, v5, vcc
	v_cndmask_b32_e64 v2, v2, v4, s[20:21]
	global_store_dwordx2 v[8:9], v[2:3], off
